# v33: v31 + non-temporal hint on the five streaming loads of mix_rwkv (read once)
# speedup vs baseline: 1.0142x; 1.0142x over previous
.LBB0_1395:
	s_waitcnt vmcnt(1)
	v_ashrrev_i32_e32 v26, 1, v4
	v_and_or_b32 v2, v7, 4, v5
	v_ashrrev_i32_e32 v27, 31, v26
	v_lshl_or_b32 v2, v2, 6, v6
	v_lshlrev_b64 v[22:23], 9, v[26:27]
	v_or_b32_e32 v22, v22, v2
	v_lshlrev_b32_e32 v9, 2, v2
	v_lshl_add_u64 v[28:29], v[22:23], 2, s[86:87]
	v_lshlrev_b64 v[22:23], 1, v[22:23]
	global_load_dwordx4 v[10:13], v9, s[16:17]
	global_load_dwordx4 v[14:17], v9, s[18:19]
	global_load_dwordx4 v[18:21], v9, s[20:21]
	v_lshl_add_u64 v[30:31], s[42:43], 0, v[22:23]
	v_lshl_add_u64 v[32:33], s[44:45], 0, v[22:23]
	v_lshl_add_u64 v[34:35], s[46:47], 0, v[22:23]
	v_lshl_add_u64 v[36:37], s[14:15], 0, v[22:23]
	global_load_dwordx4 v[22:25], v[28:29], off nt
	global_load_dwordx2 v[38:39], v[30:31], off nt
	global_load_dwordx2 v[40:41], v[32:33], off nt
	global_load_dwordx2 v[42:43], v[34:35], off nt
	global_load_dwordx2 v[44:45], v[36:37], off nt
	v_mad_i64_i32 v[26:27], s[10:11], v26, s2, v[0:1]
	v_lshlrev_b32_e32 v2, 1, v2
	v_lshl_add_u64 v[26:27], v[26:27], 0, v[2:3]
	v_add_u32_e32 v4, s4, v4
	v_cmp_lt_i32_e32 vcc, s3, v4
	s_or_b64 s[8:9], vcc, s[8:9]
	v_add_u32_e32 v7, s0, v7
	s_waitcnt vmcnt(4)
	v_add_f32_e32 v2, v22, v23
	v_add_f32_e32 v2, v2, v24
	s_waitcnt vmcnt(3)
	v_lshlrev_b32_e32 v28, 16, v38
	v_and_b32_e32 v29, 0xffff0000, v38
	s_waitcnt vmcnt(2)
	v_lshlrev_b32_e32 v32, 16, v40
	v_and_b32_e32 v33, 0xffff0000, v40
	v_add_f32_e32 v2, v2, v25
	v_lshlrev_b32_e32 v30, 16, v39
	v_and_b32_e32 v31, 0xffff0000, v39
	v_lshlrev_b32_e32 v34, 16, v41
	v_and_b32_e32 v35, 0xffff0000, v41
	v_pk_mul_f32 v[28:29], v[28:29], v[32:33]
	v_add_f32_dpp v2, v2, v2 quad_perm:[1,0,3,2] row_mask:0xf bank_mask:0xf bound_ctrl:1
	v_pk_mul_f32 v[30:31], v[30:31], v[34:35]
	v_pk_mul_f32 v[10:11], v[10:11], v[28:29]
	v_add_f32_dpp v2, v2, v2 quad_perm:[2,3,0,1] row_mask:0xf bank_mask:0xf bound_ctrl:1
	v_pk_mul_f32 v[12:13], v[12:13], v[30:31]
	v_add_f32_e32 v9, v10, v11
	v_add_f32_dpp v2, v2, v2 row_half_mirror row_mask:0xf bank_mask:0xf bound_ctrl:1
	v_add_f32_e32 v9, v9, v12
	v_add_f32_e32 v9, v13, v9
	v_add_f32_dpp v2, v2, v2 row_ror:8 row_mask:0xf bank_mask:0xf bound_ctrl:1
	v_mul_f32_e32 v2, 0x3c800000, v2
	v_add_f32_dpp v9, v9, v9 quad_perm:[1,0,3,2] row_mask:0xf bank_mask:0xf bound_ctrl:1
	v_pk_add_f32 v[10:11], v[22:23], v[2:3] op_sel_hi:[1,0] neg_lo:[0,1] neg_hi:[0,1]
	v_pk_add_f32 v[12:13], v[24:25], v[2:3] op_sel_hi:[1,0] neg_lo:[0,1] neg_hi:[0,1]
	v_add_f32_dpp v9, v9, v9 quad_perm:[2,3,0,1] row_mask:0xf bank_mask:0xf bound_ctrl:1
	v_pk_mul_f32 v[22:23], v[10:11], v[10:11]
	v_pk_mul_f32 v[24:25], v[12:13], v[12:13]
	v_add_f32_dpp v2, v9, v9 row_half_mirror row_mask:0xf bank_mask:0xf bound_ctrl:1
	v_add_f32_e32 v9, v22, v23
	v_add_f32_e32 v9, v24, v9
	v_add_f32_e32 v9, v25, v9
	s_waitcnt vmcnt(1)
	v_lshlrev_b32_e32 v36, 16, v42
	v_and_b32_e32 v37, 0xffff0000, v42
	v_add_f32_dpp v9, v9, v9 quad_perm:[1,0,3,2] row_mask:0xf bank_mask:0xf bound_ctrl:1
	v_lshlrev_b32_e32 v38, 16, v43
	v_and_b32_e32 v39, 0xffff0000, v43
	v_add_f32_dpp v9, v9, v9 quad_perm:[2,3,0,1] row_mask:0xf bank_mask:0xf bound_ctrl:1
	v_add_f32_dpp v2, v2, v2 row_ror:8 row_mask:0xf bank_mask:0xf bound_ctrl:1
	s_waitcnt vmcnt(0)
	v_lshlrev_b32_e32 v40, 16, v44
	v_add_f32_dpp v9, v9, v9 row_half_mirror row_mask:0xf bank_mask:0xf bound_ctrl:1
	v_and_b32_e32 v41, 0xffff0000, v44
	v_lshlrev_b32_e32 v42, 16, v45
	v_add_f32_dpp v9, v9, v9 row_ror:8 row_mask:0xf bank_mask:0xf bound_ctrl:1
	v_fmamk_f32 v9, v9, 0x3c800000, v8
	v_mul_f32_e32 v22, 0x4b800000, v9
	v_cmp_gt_f32_e32 vcc, s1, v9
	v_and_b32_e32 v43, 0xffff0000, v45
	s_nop 0
	v_cndmask_b32_e32 v9, v9, v22, vcc
	v_rsq_f32_e32 v9, v9
	s_nop 0
	v_mul_f32_e32 v22, 0x45800000, v9
	v_cndmask_b32_e32 v22, v9, v22, vcc
	v_pk_mul_f32 v[10:11], v[10:11], v[22:23] op_sel_hi:[1,0]
	v_pk_mul_f32 v[12:13], v[12:13], v[22:23] op_sel_hi:[1,0]
	v_pk_fma_f32 v[10:11], v[14:15], v[10:11], v[18:19]
	v_pk_fma_f32 v[12:13], v[16:17], v[12:13], v[20:21]
	v_pk_fma_f32 v[10:11], v[2:3], v[36:37], v[10:11] op_sel_hi:[0,1,1]
	v_pk_fma_f32 v[12:13], v[2:3], v[38:39], v[12:13] op_sel_hi:[0,1,1]
	v_pk_mul_f32 v[10:11], v[10:11], v[40:41]
	v_pk_mul_f32 v[12:13], v[12:13], v[42:43]
	v_cvt_pk_bf16_f32 v10, v10, v11
	v_cvt_pk_bf16_f32 v11, v12, v13
	global_store_dwordx2 v[26:27], v[10:11], off offset:1024
	s_andn2_b64 exec, exec, s[8:9]
	s_cbranch_execnz .LBB0_1395
